# best + P1 gate-image stores written through
# speedup vs baseline: 1.0068x; 1.0010x over previous
.LBB0_135:
	s_add_i32 s6, s90, -10
	v_lshl_or_b32 v138, s6, 8, v181
	v_lshl_add_u64 v[176:177], v[138:139], 2, s[48:49]
	global_load_dwordx4 v[156:159], v[176:177], off offset:16
	global_load_dwordx4 v[160:163], v[176:177], off
	global_load_dwordx4 v[226:229], v[176:177], off offset:528
	global_load_dwordx4 v[230:233], v[176:177], off offset:512
	s_lshl_b32 s7, s6, 4
	s_and_b32 s7, s7, 0x3fffffc0
	s_add_i32 s7, s7, s38
	s_lshl_b32 s7, s7, 2
	s_and_b32 s6, s6, 3
	s_or_b32 s6, s7, s6
	s_ashr_i32 s7, s6, 31
	s_lshl_b64 s[6:7], s[6:7], 16
	s_waitcnt vmcnt(2)
	v_pk_mul_f32 v[164:165], v[158:159], s[96:97] op_sel_hi:[1,0]
	v_pk_mul_f32 v[168:169], v[156:157], s[96:97] op_sel_hi:[1,0]
	s_nop 0
	s_nop 0
	v_pk_mul_f32 v[170:171], v[160:161], s[96:97] op_sel_hi:[1,0]
	v_fmamk_f32 v56, v56, 0xbfb8aa3b, v168
	v_fmamk_f32 v120, v120, 0xbfb8aa3b, v168
	v_fmamk_f32 v104, v104, 0xbfb8aa3b, v168
	v_fmamk_f32 v88, v88, 0xbfb8aa3b, v168
	v_fmamk_f32 v72, v72, 0xbfb8aa3b, v168
	v_exp_f32_e32 v56, v56
	v_fmamk_f32 v57, v57, 0xbfb8aa3b, v169
	v_fmamk_f32 v40, v40, 0xbfb8aa3b, v168
	v_fmamk_f32 v24, v24, 0xbfb8aa3b, v168
	v_fmamk_f32 v8, v8, 0xbfb8aa3b, v168
	v_pk_mul_f32 v[166:167], v[162:163], s[96:97] op_sel_hi:[1,0]
	v_exp_f32_e32 v120, v120
	v_fmamk_f32 v121, v121, 0xbfb8aa3b, v169
	v_exp_f32_e32 v104, v104
	v_fmamk_f32 v105, v105, 0xbfb8aa3b, v169
	v_exp_f32_e32 v88, v88
	v_fmamk_f32 v89, v89, 0xbfb8aa3b, v169
	v_exp_f32_e32 v72, v72
	v_fmamk_f32 v73, v73, 0xbfb8aa3b, v169
	v_exp_f32_e32 v57, v57
	v_fmamk_f32 v58, v58, 0xbfb8aa3b, v164
	v_exp_f32_e32 v40, v40
	v_fmamk_f32 v41, v41, 0xbfb8aa3b, v169
	v_exp_f32_e32 v24, v24
	v_fmamk_f32 v25, v25, 0xbfb8aa3b, v169
	v_exp_f32_e32 v8, v8
	v_fmac_f32_e32 v169, 0xbfb8aa3b, v9
	v_exp_f32_e32 v121, v121
	v_fmamk_f32 v122, v122, 0xbfb8aa3b, v164
	v_exp_f32_e32 v105, v105
	v_fmamk_f32 v106, v106, 0xbfb8aa3b, v164
	v_exp_f32_e32 v89, v89
	v_fmamk_f32 v90, v90, 0xbfb8aa3b, v164
	v_exp_f32_e32 v73, v73
	v_fmamk_f32 v74, v74, 0xbfb8aa3b, v164
	v_exp_f32_e32 v58, v58
	v_exp_f32_e32 v41, v41
	v_fmamk_f32 v42, v42, 0xbfb8aa3b, v164
	v_exp_f32_e32 v25, v25
	v_fmamk_f32 v26, v26, 0xbfb8aa3b, v164
	v_exp_f32_e32 v9, v169
	v_exp_f32_e32 v122, v122
	v_exp_f32_e32 v106, v106
	v_exp_f32_e32 v90, v90
	v_exp_f32_e32 v74, v74
	v_exp_f32_e32 v42, v42
	v_exp_f32_e32 v26, v26
	v_fmamk_f32 v10, v10, 0xbfb8aa3b, v164
	v_fmamk_f32 v56, v56, 0x3b808081, v205
	v_exp_f32_e32 v10, v10
	v_fmamk_f32 v120, v120, 0x3b808081, v205
	v_fmamk_f32 v104, v104, 0x3b808081, v205
	v_fmamk_f32 v88, v88, 0x3b808081, v205
	v_fmamk_f32 v72, v72, 0x3b808081, v205
	v_rcp_f32_e32 v56, v56
	v_fmamk_f32 v57, v57, 0x3b808081, v205
	v_fmamk_f32 v40, v40, 0x3b808081, v205
	v_fmamk_f32 v24, v24, 0x3b808081, v205
	v_fmamk_f32 v8, v8, 0x3b808081, v205
	v_rcp_f32_e32 v120, v120
	v_fmamk_f32 v121, v121, 0x3b808081, v205
	v_rcp_f32_e32 v104, v104
	v_fmamk_f32 v105, v105, 0x3b808081, v205
	v_rcp_f32_e32 v88, v88
	v_fmamk_f32 v89, v89, 0x3b808081, v205
	v_rcp_f32_e32 v72, v72
	v_fmamk_f32 v73, v73, 0x3b808081, v205
	v_rcp_f32_e32 v57, v57
	v_fmamk_f32 v58, v58, 0x3b808081, v205
	v_rcp_f32_e32 v40, v40
	v_fmamk_f32 v41, v41, 0x3b808081, v205
	v_rcp_f32_e32 v24, v24
	v_fmamk_f32 v25, v25, 0x3b808081, v205
	v_rcp_f32_e32 v8, v8
	v_fmamk_f32 v9, v9, 0x3b808081, v205
	v_rcp_f32_e32 v121, v121
	v_fmamk_f32 v122, v122, 0x3b808081, v205
	s_waitcnt vmcnt(1)
	v_pk_mul_f32 v[160:161], v[226:227], s[96:97] op_sel_hi:[1,0]
	s_waitcnt vmcnt(0)
	v_pk_mul_f32 v[162:163], v[230:231], s[96:97] op_sel_hi:[1,0]
	v_fmamk_f32 v112, v112, 0xbfb8aa3b, v160
	v_fmamk_f32 v96, v96, 0xbfb8aa3b, v160
	v_fmamk_f32 v80, v80, 0xbfb8aa3b, v160
	v_fmamk_f32 v64, v64, 0xbfb8aa3b, v160
	v_fmamk_f32 v48, v48, 0xbfb8aa3b, v160
	v_fmamk_f32 v32, v32, 0xbfb8aa3b, v160
	v_fmamk_f32 v16, v16, 0xbfb8aa3b, v160
	v_fmamk_f32 v0, v0, 0xbfb8aa3b, v160
	v_pk_mul_f32 v[156:157], v[228:229], s[96:97] op_sel_hi:[1,0]
	v_exp_f32_e32 v112, v112
	v_fmamk_f32 v113, v113, 0xbfb8aa3b, v161
	v_exp_f32_e32 v96, v96
	v_fmamk_f32 v97, v97, 0xbfb8aa3b, v161
	v_exp_f32_e32 v80, v80
	v_fmamk_f32 v81, v81, 0xbfb8aa3b, v161
	v_exp_f32_e32 v64, v64
	v_fmamk_f32 v65, v65, 0xbfb8aa3b, v161
	v_exp_f32_e32 v48, v48
	v_fmamk_f32 v49, v49, 0xbfb8aa3b, v161
	v_exp_f32_e32 v32, v32
	v_fmamk_f32 v33, v33, 0xbfb8aa3b, v161
	v_exp_f32_e32 v16, v16
	v_fmamk_f32 v17, v17, 0xbfb8aa3b, v161
	v_exp_f32_e32 v0, v0
	v_fmac_f32_e32 v161, 0xbfb8aa3b, v1
	v_exp_f32_e32 v113, v113
	v_fmamk_f32 v114, v114, 0xbfb8aa3b, v156
	v_exp_f32_e32 v97, v97
	v_fmamk_f32 v98, v98, 0xbfb8aa3b, v156
	v_exp_f32_e32 v81, v81
	v_fmamk_f32 v82, v82, 0xbfb8aa3b, v156
	v_exp_f32_e32 v65, v65
	v_fmamk_f32 v66, v66, 0xbfb8aa3b, v156
	v_exp_f32_e32 v49, v49
	v_fmamk_f32 v50, v50, 0xbfb8aa3b, v156
	v_exp_f32_e32 v33, v33
	v_fmamk_f32 v34, v34, 0xbfb8aa3b, v156
	v_exp_f32_e32 v17, v17
	v_fmamk_f32 v18, v18, 0xbfb8aa3b, v156
	v_exp_f32_e32 v1, v161
	v_exp_f32_e32 v114, v114
	v_exp_f32_e32 v98, v98
	v_exp_f32_e32 v82, v82
	v_exp_f32_e32 v66, v66
	v_exp_f32_e32 v50, v50
	v_exp_f32_e32 v34, v34
	v_exp_f32_e32 v18, v18
	v_fmamk_f32 v2, v2, 0xbfb8aa3b, v156
	v_exp_f32_e32 v2, v2
	v_fmamk_f32 v112, v112, 0x3b808081, v205
	v_fmamk_f32 v96, v96, 0x3b808081, v205
	v_fmamk_f32 v80, v80, 0x3b808081, v205
	v_fmamk_f32 v64, v64, 0x3b808081, v205
	v_fmamk_f32 v48, v48, 0x3b808081, v205
	v_fmamk_f32 v32, v32, 0x3b808081, v205
	v_fmamk_f32 v16, v16, 0x3b808081, v205
	v_fmamk_f32 v0, v0, 0x3b808081, v205
	v_rcp_f32_e32 v112, v112
	v_fmamk_f32 v113, v113, 0x3b808081, v205
	v_rcp_f32_e32 v96, v96
	v_fmamk_f32 v97, v97, 0x3b808081, v205
	v_rcp_f32_e32 v80, v80
	v_fmamk_f32 v81, v81, 0x3b808081, v205
	v_rcp_f32_e32 v64, v64
	v_fmamk_f32 v65, v65, 0x3b808081, v205
	v_rcp_f32_e32 v48, v48
	v_fmamk_f32 v49, v49, 0x3b808081, v205
	v_rcp_f32_e32 v32, v32
	v_fmamk_f32 v33, v33, 0x3b808081, v205
	v_rcp_f32_e32 v16, v16
	v_fmamk_f32 v17, v17, 0x3b808081, v205
	v_rcp_f32_e32 v0, v0
	v_fmamk_f32 v1, v1, 0x3b808081, v205
	v_rcp_f32_e32 v113, v113
	v_fmamk_f32 v114, v114, 0x3b808081, v205
	v_rcp_f32_e32 v105, v105
	v_fmamk_f32 v106, v106, 0x3b808081, v205
	v_rcp_f32_e32 v97, v97
	v_fmamk_f32 v98, v98, 0x3b808081, v205
	v_rcp_f32_e32 v89, v89
	v_fmamk_f32 v90, v90, 0x3b808081, v205
	v_rcp_f32_e32 v81, v81
	v_fmamk_f32 v82, v82, 0x3b808081, v205
	v_rcp_f32_e32 v73, v73
	v_fmamk_f32 v74, v74, 0x3b808081, v205
	v_rcp_f32_e32 v65, v65
	v_fmamk_f32 v66, v66, 0x3b808081, v205
	v_rcp_f32_e32 v58, v58
	v_rcp_f32_e32 v49, v49
	v_fmamk_f32 v50, v50, 0x3b808081, v205
	v_rcp_f32_e32 v41, v41
	v_fmamk_f32 v42, v42, 0x3b808081, v205
	v_rcp_f32_e32 v33, v33
	v_fmamk_f32 v34, v34, 0x3b808081, v205
	v_rcp_f32_e32 v25, v25
	v_fmamk_f32 v26, v26, 0x3b808081, v205
	v_rcp_f32_e32 v17, v17
	v_fmamk_f32 v18, v18, 0x3b808081, v205
	v_rcp_f32_e32 v9, v9
	v_rcp_f32_e32 v1, v1
	v_rcp_f32_e32 v122, v122
	v_rcp_f32_e32 v114, v114
	v_rcp_f32_e32 v106, v106
	v_rcp_f32_e32 v98, v98
	v_rcp_f32_e32 v90, v90
	v_rcp_f32_e32 v82, v82
	v_rcp_f32_e32 v74, v74
	v_rcp_f32_e32 v66, v66
	v_rcp_f32_e32 v50, v50
	v_rcp_f32_e32 v42, v42
	v_rcp_f32_e32 v34, v34
	v_rcp_f32_e32 v26, v26
	v_rcp_f32_e32 v18, v18
	v_fmamk_f32 v10, v10, 0x3b808081, v205
	v_fmamk_f32 v2, v2, 0x3b808081, v205
	v_max_f32_e32 v56, 1.0, v56
	v_rcp_f32_e32 v10, v10
	v_rcp_f32_e32 v2, v2
	v_max_f32_e32 v120, 1.0, v120
	v_max_f32_e32 v112, 1.0, v112
	v_max_f32_e32 v104, 1.0, v104
	v_max_f32_e32 v96, 1.0, v96
	v_max_f32_e32 v88, 1.0, v88
	v_max_f32_e32 v80, 1.0, v80
	v_max_f32_e32 v72, 1.0, v72
	v_max_f32_e32 v64, 1.0, v64
	v_fmamk_f32 v60, v60, 0xbfb8aa3b, v170
	v_rndne_f32_e32 v56, v56
	v_max_f32_e32 v57, 1.0, v57
	v_max_f32_e32 v48, 1.0, v48
	v_max_f32_e32 v40, 1.0, v40
	v_max_f32_e32 v32, 1.0, v32
	v_max_f32_e32 v24, 1.0, v24
	v_max_f32_e32 v16, 1.0, v16
	v_max_f32_e32 v8, 1.0, v8
	v_max_f32_e32 v0, 1.0, v0
	v_fmamk_f32 v124, v124, 0xbfb8aa3b, v170
	v_rndne_f32_e32 v120, v120
	v_max_f32_e32 v121, 1.0, v121
	v_fmamk_f32 v116, v116, 0xbfb8aa3b, v162
	v_rndne_f32_e32 v112, v112
	v_max_f32_e32 v113, 1.0, v113
	v_fmamk_f32 v108, v108, 0xbfb8aa3b, v170
	v_rndne_f32_e32 v104, v104
	v_max_f32_e32 v105, 1.0, v105
	v_fmamk_f32 v100, v100, 0xbfb8aa3b, v162
	v_rndne_f32_e32 v96, v96
	v_max_f32_e32 v97, 1.0, v97
	v_fmamk_f32 v92, v92, 0xbfb8aa3b, v170
	v_rndne_f32_e32 v88, v88
	v_max_f32_e32 v89, 1.0, v89
	v_fmamk_f32 v84, v84, 0xbfb8aa3b, v162
	v_rndne_f32_e32 v80, v80
	v_max_f32_e32 v81, 1.0, v81
	v_fmamk_f32 v76, v76, 0xbfb8aa3b, v170
	v_rndne_f32_e32 v72, v72
	v_max_f32_e32 v73, 1.0, v73
	v_fmamk_f32 v68, v68, 0xbfb8aa3b, v162
	v_rndne_f32_e32 v64, v64
	v_max_f32_e32 v65, 1.0, v65
	v_exp_f32_e32 v60, v60
	v_cvt_pk_u8_f32 v56, v56, 0, 0
	v_fmamk_f32 v61, v61, 0xbfb8aa3b, v171
	v_rndne_f32_e32 v57, v57
	v_max_f32_e32 v58, 1.0, v58
	v_fmamk_f32 v52, v52, 0xbfb8aa3b, v162
	v_rndne_f32_e32 v48, v48
	v_max_f32_e32 v49, 1.0, v49
	v_fmamk_f32 v44, v44, 0xbfb8aa3b, v170
	v_rndne_f32_e32 v40, v40
	v_max_f32_e32 v41, 1.0, v41
	v_fmamk_f32 v36, v36, 0xbfb8aa3b, v162
	v_rndne_f32_e32 v32, v32
	v_max_f32_e32 v33, 1.0, v33
	v_fmamk_f32 v28, v28, 0xbfb8aa3b, v170
	v_rndne_f32_e32 v24, v24
	v_max_f32_e32 v25, 1.0, v25
	v_fmamk_f32 v20, v20, 0xbfb8aa3b, v162
	v_rndne_f32_e32 v16, v16
	v_max_f32_e32 v17, 1.0, v17
	v_fmamk_f32 v12, v12, 0xbfb8aa3b, v170
	v_rndne_f32_e32 v8, v8
	v_max_f32_e32 v9, 1.0, v9
	v_fmamk_f32 v4, v4, 0xbfb8aa3b, v162
	v_rndne_f32_e32 v0, v0
	v_max_f32_e32 v1, 1.0, v1
	v_pk_mul_f32 v[158:159], v[232:233], s[96:97] op_sel_hi:[1,0]
	v_exp_f32_e32 v124, v124
	v_cvt_pk_u8_f32 v120, v120, 0, 0
	v_fmamk_f32 v125, v125, 0xbfb8aa3b, v171
	v_rndne_f32_e32 v121, v121
	v_max_f32_e32 v122, 1.0, v122
	v_exp_f32_e32 v116, v116
	v_cvt_pk_u8_f32 v112, v112, 0, 0
	v_fmamk_f32 v117, v117, 0xbfb8aa3b, v163
	v_rndne_f32_e32 v113, v113
	v_max_f32_e32 v114, 1.0, v114
	v_exp_f32_e32 v108, v108
	v_cvt_pk_u8_f32 v104, v104, 0, 0
	v_fmamk_f32 v109, v109, 0xbfb8aa3b, v171
	v_rndne_f32_e32 v105, v105
	v_max_f32_e32 v106, 1.0, v106
	v_exp_f32_e32 v100, v100
	v_cvt_pk_u8_f32 v96, v96, 0, 0
	v_fmamk_f32 v101, v101, 0xbfb8aa3b, v163
	v_rndne_f32_e32 v97, v97
	v_max_f32_e32 v98, 1.0, v98
	v_exp_f32_e32 v92, v92
	v_cvt_pk_u8_f32 v88, v88, 0, 0
	v_fmamk_f32 v93, v93, 0xbfb8aa3b, v171
	v_rndne_f32_e32 v89, v89
	v_max_f32_e32 v90, 1.0, v90
	v_exp_f32_e32 v84, v84
	v_cvt_pk_u8_f32 v80, v80, 0, 0
	v_fmamk_f32 v85, v85, 0xbfb8aa3b, v163
	v_rndne_f32_e32 v81, v81
	v_max_f32_e32 v82, 1.0, v82
	v_exp_f32_e32 v76, v76
	v_cvt_pk_u8_f32 v72, v72, 0, 0
	v_fmamk_f32 v77, v77, 0xbfb8aa3b, v171
	v_rndne_f32_e32 v73, v73
	v_max_f32_e32 v74, 1.0, v74
	v_exp_f32_e32 v68, v68
	v_cvt_pk_u8_f32 v64, v64, 0, 0
	v_fmamk_f32 v69, v69, 0xbfb8aa3b, v163
	v_rndne_f32_e32 v65, v65
	v_max_f32_e32 v66, 1.0, v66
	v_exp_f32_e32 v61, v61
	v_cvt_pk_u8_f32 v56, v57, 1, v56
	v_fmamk_f32 v57, v62, 0xbfb8aa3b, v166
	v_rndne_f32_e32 v58, v58
	v_exp_f32_e32 v52, v52
	v_cvt_pk_u8_f32 v48, v48, 0, 0
	v_fmamk_f32 v53, v53, 0xbfb8aa3b, v163
	v_rndne_f32_e32 v49, v49
	v_max_f32_e32 v50, 1.0, v50
	v_exp_f32_e32 v44, v44
	v_cvt_pk_u8_f32 v40, v40, 0, 0
	v_fmamk_f32 v45, v45, 0xbfb8aa3b, v171
	v_rndne_f32_e32 v41, v41
	v_max_f32_e32 v42, 1.0, v42
	v_exp_f32_e32 v36, v36
	v_cvt_pk_u8_f32 v32, v32, 0, 0
	v_fmamk_f32 v37, v37, 0xbfb8aa3b, v163
	v_rndne_f32_e32 v33, v33
	v_max_f32_e32 v34, 1.0, v34
	v_exp_f32_e32 v28, v28
	v_cvt_pk_u8_f32 v24, v24, 0, 0
	v_fmamk_f32 v29, v29, 0xbfb8aa3b, v171
	v_rndne_f32_e32 v25, v25
	v_max_f32_e32 v26, 1.0, v26
	v_exp_f32_e32 v20, v20
	v_cvt_pk_u8_f32 v16, v16, 0, 0
	v_fmamk_f32 v21, v21, 0xbfb8aa3b, v163
	v_rndne_f32_e32 v17, v17
	v_max_f32_e32 v18, 1.0, v18
	v_exp_f32_e32 v12, v12
	v_cvt_pk_u8_f32 v8, v8, 0, 0
	v_fmac_f32_e32 v171, 0xbfb8aa3b, v13
	v_rndne_f32_e32 v9, v9
	v_exp_f32_e32 v4, v4
	v_cvt_pk_u8_f32 v0, v0, 0, 0
	v_fmac_f32_e32 v163, 0xbfb8aa3b, v5
	v_rndne_f32_e32 v1, v1
	v_exp_f32_e32 v125, v125
	v_cvt_pk_u8_f32 v120, v121, 1, v120
	v_fmamk_f32 v121, v126, 0xbfb8aa3b, v166
	v_rndne_f32_e32 v122, v122
	v_exp_f32_e32 v117, v117
	v_cvt_pk_u8_f32 v112, v113, 1, v112
	v_fmamk_f32 v113, v118, 0xbfb8aa3b, v158
	v_rndne_f32_e32 v114, v114
	v_exp_f32_e32 v109, v109
	v_cvt_pk_u8_f32 v104, v105, 1, v104
	v_fmamk_f32 v105, v110, 0xbfb8aa3b, v166
	v_rndne_f32_e32 v106, v106
	v_exp_f32_e32 v101, v101
	v_cvt_pk_u8_f32 v96, v97, 1, v96
	v_fmamk_f32 v97, v102, 0xbfb8aa3b, v158
	v_rndne_f32_e32 v98, v98
	v_exp_f32_e32 v93, v93
	v_cvt_pk_u8_f32 v88, v89, 1, v88
	v_fmamk_f32 v89, v94, 0xbfb8aa3b, v166
	v_rndne_f32_e32 v90, v90
	v_exp_f32_e32 v85, v85
	v_cvt_pk_u8_f32 v80, v81, 1, v80
	v_fmamk_f32 v81, v86, 0xbfb8aa3b, v158
	v_rndne_f32_e32 v82, v82
	v_exp_f32_e32 v77, v77
	v_cvt_pk_u8_f32 v72, v73, 1, v72
	v_fmamk_f32 v73, v78, 0xbfb8aa3b, v166
	v_rndne_f32_e32 v74, v74
	v_exp_f32_e32 v69, v69
	v_cvt_pk_u8_f32 v64, v65, 1, v64
	v_fmamk_f32 v65, v70, 0xbfb8aa3b, v158
	v_rndne_f32_e32 v66, v66
	v_exp_f32_e32 v57, v57
	v_cvt_pk_u8_f32 v58, v58, 2, v56
	v_fmamk_f32 v56, v63, 0xbfb8aa3b, v167
	v_fmamk_f32 v59, v59, 0xbfb8aa3b, v165
	v_exp_f32_e32 v53, v53
	v_cvt_pk_u8_f32 v48, v49, 1, v48
	v_fmamk_f32 v49, v54, 0xbfb8aa3b, v158
	v_rndne_f32_e32 v50, v50
	v_fmamk_f32 v51, v51, 0xbfb8aa3b, v157
	v_exp_f32_e32 v45, v45
	v_cvt_pk_u8_f32 v40, v41, 1, v40
	v_fmamk_f32 v41, v46, 0xbfb8aa3b, v166
	v_rndne_f32_e32 v42, v42
	v_exp_f32_e32 v37, v37
	v_cvt_pk_u8_f32 v32, v33, 1, v32
	v_fmamk_f32 v33, v38, 0xbfb8aa3b, v158
	v_rndne_f32_e32 v34, v34
	v_exp_f32_e32 v29, v29
	v_cvt_pk_u8_f32 v24, v25, 1, v24
	v_fmamk_f32 v25, v30, 0xbfb8aa3b, v166
	v_rndne_f32_e32 v26, v26
	v_exp_f32_e32 v21, v21
	v_cvt_pk_u8_f32 v16, v17, 1, v16
	v_fmamk_f32 v17, v22, 0xbfb8aa3b, v158
	v_rndne_f32_e32 v18, v18
	v_exp_f32_e32 v13, v171
	v_cvt_pk_u8_f32 v8, v9, 1, v8
	v_fmamk_f32 v9, v14, 0xbfb8aa3b, v166
	v_max_f32_e32 v10, 1.0, v10
	v_exp_f32_e32 v5, v163
	v_cvt_pk_u8_f32 v0, v1, 1, v0
	v_fmamk_f32 v1, v6, 0xbfb8aa3b, v158
	v_max_f32_e32 v2, 1.0, v2
	v_exp_f32_e32 v121, v121
	v_cvt_pk_u8_f32 v122, v122, 2, v120
	v_fmamk_f32 v120, v127, 0xbfb8aa3b, v167
	v_fmamk_f32 v123, v123, 0xbfb8aa3b, v165
	v_exp_f32_e32 v113, v113
	v_cvt_pk_u8_f32 v112, v114, 2, v112
	v_fmamk_f32 v114, v119, 0xbfb8aa3b, v159
	v_fmamk_f32 v115, v115, 0xbfb8aa3b, v157
	v_exp_f32_e32 v105, v105
	v_cvt_pk_u8_f32 v106, v106, 2, v104
	v_fmamk_f32 v104, v111, 0xbfb8aa3b, v167
	v_fmamk_f32 v107, v107, 0xbfb8aa3b, v165
	v_exp_f32_e32 v97, v97
	v_cvt_pk_u8_f32 v96, v98, 2, v96
	v_fmamk_f32 v98, v103, 0xbfb8aa3b, v159
	v_fmamk_f32 v99, v99, 0xbfb8aa3b, v157
	v_exp_f32_e32 v89, v89
	v_cvt_pk_u8_f32 v90, v90, 2, v88
	v_fmamk_f32 v88, v95, 0xbfb8aa3b, v167
	v_fmamk_f32 v91, v91, 0xbfb8aa3b, v165
	v_exp_f32_e32 v81, v81
	v_cvt_pk_u8_f32 v80, v82, 2, v80
	v_fmamk_f32 v82, v87, 0xbfb8aa3b, v159
	v_fmamk_f32 v83, v83, 0xbfb8aa3b, v157
	v_exp_f32_e32 v73, v73
	v_cvt_pk_u8_f32 v74, v74, 2, v72
	v_fmamk_f32 v72, v79, 0xbfb8aa3b, v167
	v_fmamk_f32 v75, v75, 0xbfb8aa3b, v165
	v_exp_f32_e32 v65, v65
	v_cvt_pk_u8_f32 v64, v66, 2, v64
	v_fmamk_f32 v66, v71, 0xbfb8aa3b, v159
	v_fmamk_f32 v67, v67, 0xbfb8aa3b, v157
	v_exp_f32_e32 v56, v56
	v_exp_f32_e32 v59, v59
	v_exp_f32_e32 v49, v49
	v_cvt_pk_u8_f32 v48, v50, 2, v48
	v_fmamk_f32 v50, v55, 0xbfb8aa3b, v159
	v_exp_f32_e32 v51, v51
	v_exp_f32_e32 v41, v41
	v_cvt_pk_u8_f32 v42, v42, 2, v40
	v_fmamk_f32 v40, v47, 0xbfb8aa3b, v167
	v_fmamk_f32 v43, v43, 0xbfb8aa3b, v165
	v_exp_f32_e32 v33, v33
	v_cvt_pk_u8_f32 v32, v34, 2, v32
	v_fmamk_f32 v34, v39, 0xbfb8aa3b, v159
	v_fmamk_f32 v35, v35, 0xbfb8aa3b, v157
	v_exp_f32_e32 v25, v25
	v_cvt_pk_u8_f32 v26, v26, 2, v24
	v_fmamk_f32 v24, v31, 0xbfb8aa3b, v167
	v_fmamk_f32 v27, v27, 0xbfb8aa3b, v165
	v_exp_f32_e32 v17, v17
	v_cvt_pk_u8_f32 v16, v18, 2, v16
	v_fmamk_f32 v18, v23, 0xbfb8aa3b, v159
	v_fmamk_f32 v19, v19, 0xbfb8aa3b, v157
	v_exp_f32_e32 v9, v9
	v_rndne_f32_e32 v10, v10
	v_fmac_f32_e32 v167, 0xbfb8aa3b, v15
	v_fmac_f32_e32 v165, 0xbfb8aa3b, v11
	v_exp_f32_e32 v1, v1
	v_rndne_f32_e32 v2, v2
	v_fmac_f32_e32 v159, 0xbfb8aa3b, v7
	v_fmac_f32_e32 v157, 0xbfb8aa3b, v3
	v_exp_f32_e32 v120, v120
	v_exp_f32_e32 v123, v123
	v_exp_f32_e32 v114, v114
	v_exp_f32_e32 v115, v115
	v_exp_f32_e32 v104, v104
	v_exp_f32_e32 v107, v107
	v_exp_f32_e32 v98, v98
	v_exp_f32_e32 v99, v99
	v_exp_f32_e32 v88, v88
	v_exp_f32_e32 v91, v91
	v_exp_f32_e32 v82, v82
	v_exp_f32_e32 v83, v83
	v_exp_f32_e32 v72, v72
	v_exp_f32_e32 v75, v75
	v_exp_f32_e32 v66, v66
	v_exp_f32_e32 v67, v67
	v_fmamk_f32 v60, v60, 0x3b808081, v205
	v_exp_f32_e32 v50, v50
	v_exp_f32_e32 v40, v40
	v_exp_f32_e32 v43, v43
	v_exp_f32_e32 v34, v34
	v_exp_f32_e32 v35, v35
	v_exp_f32_e32 v24, v24
	v_exp_f32_e32 v27, v27
	v_exp_f32_e32 v18, v18
	v_exp_f32_e32 v19, v19
	v_cvt_pk_u8_f32 v10, v10, 2, v8
	v_exp_f32_e32 v8, v167
	v_exp_f32_e32 v11, v165
	v_cvt_pk_u8_f32 v0, v2, 2, v0
	v_exp_f32_e32 v2, v159
	v_exp_f32_e32 v3, v157
	v_fmamk_f32 v124, v124, 0x3b808081, v205
	v_fmamk_f32 v116, v116, 0x3b808081, v205
	v_fmamk_f32 v108, v108, 0x3b808081, v205
	v_fmamk_f32 v100, v100, 0x3b808081, v205
	v_fmamk_f32 v92, v92, 0x3b808081, v205
	v_fmamk_f32 v84, v84, 0x3b808081, v205
	v_fmamk_f32 v76, v76, 0x3b808081, v205
	v_fmamk_f32 v68, v68, 0x3b808081, v205
	v_rcp_f32_e32 v60, v60
	v_fmamk_f32 v61, v61, 0x3b808081, v205
	v_fmamk_f32 v52, v52, 0x3b808081, v205
	v_fmamk_f32 v44, v44, 0x3b808081, v205
	v_fmamk_f32 v36, v36, 0x3b808081, v205
	v_fmamk_f32 v28, v28, 0x3b808081, v205
	v_fmamk_f32 v20, v20, 0x3b808081, v205
	v_fmamk_f32 v12, v12, 0x3b808081, v205
	v_fmamk_f32 v4, v4, 0x3b808081, v205
	v_rcp_f32_e32 v124, v124
	v_fmamk_f32 v125, v125, 0x3b808081, v205
	v_rcp_f32_e32 v116, v116
	v_fmamk_f32 v117, v117, 0x3b808081, v205
	v_rcp_f32_e32 v108, v108
	v_fmamk_f32 v109, v109, 0x3b808081, v205
	v_rcp_f32_e32 v100, v100
	v_fmamk_f32 v101, v101, 0x3b808081, v205
	v_rcp_f32_e32 v92, v92
	v_fmamk_f32 v93, v93, 0x3b808081, v205
	v_rcp_f32_e32 v84, v84
	v_fmamk_f32 v85, v85, 0x3b808081, v205
	v_rcp_f32_e32 v76, v76
	v_fmamk_f32 v77, v77, 0x3b808081, v205
	v_rcp_f32_e32 v68, v68
	v_fmamk_f32 v69, v69, 0x3b808081, v205
	v_rcp_f32_e32 v61, v61
	v_fmamk_f32 v57, v57, 0x3b808081, v205
	v_rcp_f32_e32 v52, v52
	v_fmamk_f32 v53, v53, 0x3b808081, v205
	v_rcp_f32_e32 v44, v44
	v_fmamk_f32 v45, v45, 0x3b808081, v205
	v_rcp_f32_e32 v36, v36
	v_fmamk_f32 v37, v37, 0x3b808081, v205
	v_rcp_f32_e32 v28, v28
	v_fmamk_f32 v29, v29, 0x3b808081, v205
	v_rcp_f32_e32 v20, v20
	v_fmamk_f32 v21, v21, 0x3b808081, v205
	v_rcp_f32_e32 v12, v12
	v_fmamk_f32 v13, v13, 0x3b808081, v205
	v_rcp_f32_e32 v4, v4
	v_fmamk_f32 v5, v5, 0x3b808081, v205
	v_rcp_f32_e32 v125, v125
	v_fmamk_f32 v121, v121, 0x3b808081, v205
	v_rcp_f32_e32 v117, v117
	v_fmamk_f32 v113, v113, 0x3b808081, v205
	v_rcp_f32_e32 v109, v109
	v_fmamk_f32 v105, v105, 0x3b808081, v205
	v_rcp_f32_e32 v101, v101
	v_fmamk_f32 v97, v97, 0x3b808081, v205
	v_rcp_f32_e32 v93, v93
	v_fmamk_f32 v89, v89, 0x3b808081, v205
	v_rcp_f32_e32 v85, v85
	v_fmamk_f32 v81, v81, 0x3b808081, v205
	v_rcp_f32_e32 v77, v77
	v_fmamk_f32 v73, v73, 0x3b808081, v205
	v_rcp_f32_e32 v69, v69
	v_fmamk_f32 v65, v65, 0x3b808081, v205
	v_rcp_f32_e32 v57, v57
	v_fmamk_f32 v56, v56, 0x3b808081, v205
	v_fmamk_f32 v59, v59, 0x3b808081, v205
	v_rcp_f32_e32 v53, v53
	v_fmamk_f32 v49, v49, 0x3b808081, v205
	v_fmamk_f32 v51, v51, 0x3b808081, v205
	v_rcp_f32_e32 v45, v45
	v_fmamk_f32 v41, v41, 0x3b808081, v205
	v_rcp_f32_e32 v37, v37
	v_fmamk_f32 v33, v33, 0x3b808081, v205
	v_rcp_f32_e32 v29, v29
	v_fmamk_f32 v25, v25, 0x3b808081, v205
	v_rcp_f32_e32 v21, v21
	v_fmamk_f32 v17, v17, 0x3b808081, v205
	v_rcp_f32_e32 v13, v13
	v_fmamk_f32 v9, v9, 0x3b808081, v205
	v_rcp_f32_e32 v5, v5
	v_fmamk_f32 v1, v1, 0x3b808081, v205
	v_rcp_f32_e32 v121, v121
	v_fmamk_f32 v120, v120, 0x3b808081, v205
	v_fmamk_f32 v123, v123, 0x3b808081, v205
	v_rcp_f32_e32 v113, v113
	v_fmamk_f32 v114, v114, 0x3b808081, v205
	v_fmamk_f32 v115, v115, 0x3b808081, v205
	v_rcp_f32_e32 v105, v105
	v_fmamk_f32 v104, v104, 0x3b808081, v205
	v_fmamk_f32 v107, v107, 0x3b808081, v205
	v_rcp_f32_e32 v97, v97
	v_fmamk_f32 v98, v98, 0x3b808081, v205
	v_fmamk_f32 v99, v99, 0x3b808081, v205
	v_rcp_f32_e32 v89, v89
	v_fmamk_f32 v88, v88, 0x3b808081, v205
	v_fmamk_f32 v91, v91, 0x3b808081, v205
	v_rcp_f32_e32 v81, v81
	v_fmamk_f32 v82, v82, 0x3b808081, v205
	v_fmamk_f32 v83, v83, 0x3b808081, v205
	v_rcp_f32_e32 v73, v73
	v_fmamk_f32 v72, v72, 0x3b808081, v205
	v_fmamk_f32 v75, v75, 0x3b808081, v205
	v_rcp_f32_e32 v65, v65
	v_fmamk_f32 v66, v66, 0x3b808081, v205
	v_fmamk_f32 v67, v67, 0x3b808081, v205
	v_rcp_f32_e32 v56, v56
	v_rcp_f32_e32 v59, v59
	v_rcp_f32_e32 v49, v49
	v_fmamk_f32 v50, v50, 0x3b808081, v205
	v_rcp_f32_e32 v51, v51
	v_rcp_f32_e32 v41, v41
	v_fmamk_f32 v40, v40, 0x3b808081, v205
	v_fmamk_f32 v43, v43, 0x3b808081, v205
	v_rcp_f32_e32 v33, v33
	v_fmamk_f32 v34, v34, 0x3b808081, v205
	v_fmamk_f32 v35, v35, 0x3b808081, v205
	v_rcp_f32_e32 v25, v25
	v_fmamk_f32 v24, v24, 0x3b808081, v205
	v_fmamk_f32 v27, v27, 0x3b808081, v205
	v_rcp_f32_e32 v17, v17
	v_fmamk_f32 v18, v18, 0x3b808081, v205
	v_fmamk_f32 v19, v19, 0x3b808081, v205
	v_rcp_f32_e32 v9, v9
	v_fmamk_f32 v8, v8, 0x3b808081, v205
	v_fmamk_f32 v11, v11, 0x3b808081, v205
	v_rcp_f32_e32 v1, v1
	v_fmamk_f32 v2, v2, 0x3b808081, v205
	v_fmamk_f32 v3, v3, 0x3b808081, v205
	v_rcp_f32_e32 v120, v120
	v_rcp_f32_e32 v123, v123
	v_rcp_f32_e32 v114, v114
	v_rcp_f32_e32 v115, v115
	v_rcp_f32_e32 v104, v104
	v_rcp_f32_e32 v107, v107
	v_rcp_f32_e32 v98, v98
	v_rcp_f32_e32 v99, v99
	v_rcp_f32_e32 v88, v88
	v_rcp_f32_e32 v91, v91
	v_rcp_f32_e32 v82, v82
	v_rcp_f32_e32 v83, v83
	v_rcp_f32_e32 v72, v72
	v_rcp_f32_e32 v75, v75
	v_rcp_f32_e32 v66, v66
	v_rcp_f32_e32 v67, v67
	v_max_f32_e32 v60, 1.0, v60
	v_rcp_f32_e32 v50, v50
	v_rcp_f32_e32 v40, v40
	v_rcp_f32_e32 v43, v43
	v_rcp_f32_e32 v34, v34
	v_rcp_f32_e32 v35, v35
	v_rcp_f32_e32 v24, v24
	v_rcp_f32_e32 v27, v27
	v_rcp_f32_e32 v18, v18
	v_rcp_f32_e32 v19, v19
	v_rcp_f32_e32 v8, v8
	v_rcp_f32_e32 v11, v11
	v_rcp_f32_e32 v2, v2
	v_rcp_f32_e32 v3, v3
	v_max_f32_e32 v124, 1.0, v124
	v_max_f32_e32 v116, 1.0, v116
	v_max_f32_e32 v108, 1.0, v108
	v_max_f32_e32 v100, 1.0, v100
	v_max_f32_e32 v92, 1.0, v92
	v_max_f32_e32 v84, 1.0, v84
	v_max_f32_e32 v76, 1.0, v76
	v_max_f32_e32 v68, 1.0, v68
	v_rndne_f32_e32 v60, v60
	v_max_f32_e32 v61, 1.0, v61
	v_max_f32_e32 v52, 1.0, v52
	v_max_f32_e32 v44, 1.0, v44
	v_max_f32_e32 v36, 1.0, v36
	v_max_f32_e32 v28, 1.0, v28
	v_max_f32_e32 v20, 1.0, v20
	v_max_f32_e32 v12, 1.0, v12
	v_max_f32_e32 v4, 1.0, v4
	v_rndne_f32_e32 v124, v124
	v_max_f32_e32 v125, 1.0, v125
	v_rndne_f32_e32 v116, v116
	v_max_f32_e32 v117, 1.0, v117
	v_rndne_f32_e32 v108, v108
	v_max_f32_e32 v109, 1.0, v109
	v_rndne_f32_e32 v100, v100
	v_max_f32_e32 v101, 1.0, v101
	v_rndne_f32_e32 v92, v92
	v_max_f32_e32 v93, 1.0, v93
	v_rndne_f32_e32 v84, v84
	v_max_f32_e32 v85, 1.0, v85
	v_rndne_f32_e32 v76, v76
	v_max_f32_e32 v77, 1.0, v77
	v_rndne_f32_e32 v68, v68
	v_max_f32_e32 v69, 1.0, v69
	v_cvt_pk_u8_f32 v60, v60, 0, 0
	v_rndne_f32_e32 v61, v61
	v_max_f32_e32 v57, 1.0, v57
	v_rndne_f32_e32 v52, v52
	v_max_f32_e32 v53, 1.0, v53
	v_rndne_f32_e32 v44, v44
	v_max_f32_e32 v45, 1.0, v45
	v_rndne_f32_e32 v36, v36
	v_max_f32_e32 v37, 1.0, v37
	v_rndne_f32_e32 v28, v28
	v_max_f32_e32 v29, 1.0, v29
	v_rndne_f32_e32 v20, v20
	v_max_f32_e32 v21, 1.0, v21
	v_rndne_f32_e32 v12, v12
	v_max_f32_e32 v13, 1.0, v13
	v_rndne_f32_e32 v4, v4
	v_max_f32_e32 v5, 1.0, v5
	v_cvt_pk_u8_f32 v124, v124, 0, 0
	v_rndne_f32_e32 v125, v125
	v_max_f32_e32 v121, 1.0, v121
	v_cvt_pk_u8_f32 v116, v116, 0, 0
	v_rndne_f32_e32 v117, v117
	v_max_f32_e32 v113, 1.0, v113
	v_cvt_pk_u8_f32 v108, v108, 0, 0
	v_rndne_f32_e32 v109, v109
	v_max_f32_e32 v105, 1.0, v105
	v_cvt_pk_u8_f32 v100, v100, 0, 0
	v_rndne_f32_e32 v101, v101
	v_max_f32_e32 v97, 1.0, v97
	v_cvt_pk_u8_f32 v92, v92, 0, 0
	v_rndne_f32_e32 v93, v93
	v_max_f32_e32 v89, 1.0, v89
	v_cvt_pk_u8_f32 v84, v84, 0, 0
	v_rndne_f32_e32 v85, v85
	v_max_f32_e32 v81, 1.0, v81
	v_cvt_pk_u8_f32 v76, v76, 0, 0
	v_rndne_f32_e32 v77, v77
	v_max_f32_e32 v73, 1.0, v73
	v_cvt_pk_u8_f32 v68, v68, 0, 0
	v_rndne_f32_e32 v69, v69
	v_max_f32_e32 v65, 1.0, v65
	v_cvt_pk_u8_f32 v60, v61, 1, v60
	v_rndne_f32_e32 v57, v57
	v_max_f32_e32 v56, 1.0, v56
	v_max_f32_e32 v59, 1.0, v59
	v_cvt_pk_u8_f32 v52, v52, 0, 0
	v_rndne_f32_e32 v53, v53
	v_max_f32_e32 v49, 1.0, v49
	v_max_f32_e32 v51, 1.0, v51
	v_cvt_pk_u8_f32 v44, v44, 0, 0
	v_rndne_f32_e32 v45, v45
	v_max_f32_e32 v41, 1.0, v41
	v_cvt_pk_u8_f32 v36, v36, 0, 0
	v_rndne_f32_e32 v37, v37
	v_max_f32_e32 v33, 1.0, v33
	v_cvt_pk_u8_f32 v28, v28, 0, 0
	v_rndne_f32_e32 v29, v29
	v_max_f32_e32 v25, 1.0, v25
	v_cvt_pk_u8_f32 v20, v20, 0, 0
	v_rndne_f32_e32 v21, v21
	v_max_f32_e32 v17, 1.0, v17
	v_cvt_pk_u8_f32 v12, v12, 0, 0
	v_rndne_f32_e32 v13, v13
	v_max_f32_e32 v9, 1.0, v9
	v_cvt_pk_u8_f32 v4, v4, 0, 0
	v_rndne_f32_e32 v5, v5
	v_max_f32_e32 v1, 1.0, v1
	v_lshl_add_u64 v[172:173], v[140:141], 0, s[6:7]
	v_cvt_pk_u8_f32 v124, v125, 1, v124
	v_rndne_f32_e32 v121, v121
	v_max_f32_e32 v120, 1.0, v120
	v_max_f32_e32 v123, 1.0, v123
	v_cvt_pk_u8_f32 v116, v117, 1, v116
	v_rndne_f32_e32 v113, v113
	v_max_f32_e32 v114, 1.0, v114
	v_max_f32_e32 v115, 1.0, v115
	v_cvt_pk_u8_f32 v108, v109, 1, v108
	v_rndne_f32_e32 v105, v105
	v_max_f32_e32 v104, 1.0, v104
	v_max_f32_e32 v107, 1.0, v107
	v_cvt_pk_u8_f32 v100, v101, 1, v100
	v_rndne_f32_e32 v97, v97
	v_max_f32_e32 v98, 1.0, v98
	v_max_f32_e32 v99, 1.0, v99
	v_cvt_pk_u8_f32 v92, v93, 1, v92
	v_rndne_f32_e32 v89, v89
	v_max_f32_e32 v88, 1.0, v88
	v_max_f32_e32 v91, 1.0, v91
	v_cvt_pk_u8_f32 v84, v85, 1, v84
	v_rndne_f32_e32 v81, v81
	v_max_f32_e32 v82, 1.0, v82
	v_max_f32_e32 v83, 1.0, v83
	v_cvt_pk_u8_f32 v76, v77, 1, v76
	v_rndne_f32_e32 v73, v73
	v_max_f32_e32 v72, 1.0, v72
	v_max_f32_e32 v75, 1.0, v75
	v_cvt_pk_u8_f32 v68, v69, 1, v68
	v_rndne_f32_e32 v65, v65
	v_max_f32_e32 v66, 1.0, v66
	v_max_f32_e32 v67, 1.0, v67
	v_cvt_pk_u8_f32 v57, v57, 2, v60
	v_rndne_f32_e32 v56, v56
	v_rndne_f32_e32 v59, v59
	v_cvt_pk_u8_f32 v52, v53, 1, v52
	v_rndne_f32_e32 v49, v49
	v_max_f32_e32 v50, 1.0, v50
	v_rndne_f32_e32 v51, v51
	s_movk_i32 s6, 0x1000
	v_cvt_pk_u8_f32 v44, v45, 1, v44
	v_rndne_f32_e32 v41, v41
	v_max_f32_e32 v40, 1.0, v40
	v_max_f32_e32 v43, 1.0, v43
	v_cvt_pk_u8_f32 v36, v37, 1, v36
	v_rndne_f32_e32 v33, v33
	v_max_f32_e32 v34, 1.0, v34
	v_max_f32_e32 v35, 1.0, v35
	v_cvt_pk_u8_f32 v28, v29, 1, v28
	v_rndne_f32_e32 v25, v25
	v_max_f32_e32 v24, 1.0, v24
	v_max_f32_e32 v27, 1.0, v27
	v_cvt_pk_u8_f32 v20, v21, 1, v20
	v_rndne_f32_e32 v17, v17
	v_max_f32_e32 v18, 1.0, v18
	v_max_f32_e32 v19, 1.0, v19
	v_cvt_pk_u8_f32 v12, v13, 1, v12
	v_rndne_f32_e32 v9, v9
	v_max_f32_e32 v8, 1.0, v8
	v_max_f32_e32 v11, 1.0, v11
	v_cvt_pk_u8_f32 v4, v5, 1, v4
	v_rndne_f32_e32 v1, v1
	v_max_f32_e32 v2, 1.0, v2
	v_max_f32_e32 v3, 1.0, v3
	v_cvt_pk_u8_f32 v121, v121, 2, v124
	v_rndne_f32_e32 v120, v120
	v_rndne_f32_e32 v123, v123
	v_cvt_pk_u8_f32 v113, v113, 2, v116
	v_rndne_f32_e32 v114, v114
	v_rndne_f32_e32 v115, v115
	v_cvt_pk_u8_f32 v105, v105, 2, v108
	v_rndne_f32_e32 v104, v104
	v_rndne_f32_e32 v107, v107
	v_cvt_pk_u8_f32 v97, v97, 2, v100
	v_rndne_f32_e32 v98, v98
	v_rndne_f32_e32 v99, v99
	v_cvt_pk_u8_f32 v89, v89, 2, v92
	v_rndne_f32_e32 v88, v88
	v_rndne_f32_e32 v91, v91
	v_cvt_pk_u8_f32 v81, v81, 2, v84
	v_rndne_f32_e32 v82, v82
	v_rndne_f32_e32 v83, v83
	v_cvt_pk_u8_f32 v73, v73, 2, v76
	v_rndne_f32_e32 v72, v72
	v_rndne_f32_e32 v75, v75
	v_cvt_pk_u8_f32 v65, v65, 2, v68
	v_rndne_f32_e32 v66, v66
	v_rndne_f32_e32 v67, v67
	v_cvt_pk_u8_f32 v56, v56, 3, v57
	v_cvt_pk_u8_f32 v57, v59, 3, v58
	v_cvt_pk_u8_f32 v49, v49, 2, v52
	v_rndne_f32_e32 v50, v50
	v_cvt_pk_u8_f32 v59, v51, 3, v48
	v_add_co_u32_e32 v48, vcc, s6, v172
	v_cvt_pk_u8_f32 v41, v41, 2, v44
	v_rndne_f32_e32 v40, v40
	v_rndne_f32_e32 v43, v43
	v_cvt_pk_u8_f32 v33, v33, 2, v36
	v_rndne_f32_e32 v34, v34
	v_rndne_f32_e32 v35, v35
	v_cvt_pk_u8_f32 v25, v25, 2, v28
	v_rndne_f32_e32 v24, v24
	v_rndne_f32_e32 v27, v27
	v_cvt_pk_u8_f32 v17, v17, 2, v20
	v_rndne_f32_e32 v18, v18
	v_rndne_f32_e32 v19, v19
	v_cvt_pk_u8_f32 v9, v9, 2, v12
	v_rndne_f32_e32 v8, v8
	v_rndne_f32_e32 v11, v11
	v_cvt_pk_u8_f32 v1, v1, 2, v4
	v_rndne_f32_e32 v2, v2
	v_rndne_f32_e32 v3, v3
	v_cvt_pk_u8_f32 v120, v120, 3, v121
	v_cvt_pk_u8_f32 v121, v123, 3, v122
	v_cvt_pk_u8_f32 v122, v114, 3, v113
	v_cvt_pk_u8_f32 v123, v115, 3, v112
	v_cvt_pk_u8_f32 v104, v104, 3, v105
	v_cvt_pk_u8_f32 v105, v107, 3, v106
	v_cvt_pk_u8_f32 v106, v98, 3, v97
	v_cvt_pk_u8_f32 v107, v99, 3, v96
	v_cvt_pk_u8_f32 v88, v88, 3, v89
	v_cvt_pk_u8_f32 v89, v91, 3, v90
	v_cvt_pk_u8_f32 v90, v82, 3, v81
	v_cvt_pk_u8_f32 v91, v83, 3, v80
	v_cvt_pk_u8_f32 v72, v72, 3, v73
	v_cvt_pk_u8_f32 v73, v75, 3, v74
	v_cvt_pk_u8_f32 v74, v66, 3, v65
	v_cvt_pk_u8_f32 v75, v67, 3, v64
	v_cvt_pk_u8_f32 v58, v50, 3, v49
	v_addc_co_u32_e32 v49, vcc, 0, v173, vcc
	v_cvt_pk_u8_f32 v40, v40, 3, v41
	v_cvt_pk_u8_f32 v41, v43, 3, v42
	v_cvt_pk_u8_f32 v42, v34, 3, v33
	v_cvt_pk_u8_f32 v43, v35, 3, v32
	v_cvt_pk_u8_f32 v24, v24, 3, v25
	v_cvt_pk_u8_f32 v25, v27, 3, v26
	v_cvt_pk_u8_f32 v26, v18, 3, v17
	v_cvt_pk_u8_f32 v27, v19, 3, v16
	v_cvt_pk_u8_f32 v8, v8, 3, v9
	v_cvt_pk_u8_f32 v9, v11, 3, v10
	v_cvt_pk_u8_f32 v10, v2, 3, v1
	v_cvt_pk_u8_f32 v11, v3, 3, v0
	global_store_dwordx4 v[172:173], v[120:123], off sc1
	global_store_dwordx4 v[172:173], v[104:107], off offset:1024 sc1
	global_store_dwordx4 v[172:173], v[88:91], off offset:2048 sc1
	global_store_dwordx4 v[172:173], v[72:75], off offset:3072 sc1
	global_store_dwordx4 v[48:49], v[56:59], off sc1
	global_store_dwordx4 v[48:49], v[40:43], off offset:1024 sc1
	global_store_dwordx4 v[48:49], v[24:27], off offset:2048 sc1
	global_store_dwordx4 v[48:49], v[8:11], off offset:3072 sc1
